# proj-phase 16-byte final-output stores: write-through plus non-temporal
# speedup vs baseline: 1.0129x; 1.0129x over previous
;     __device__ __forceinline__ void kvout(int row, int c, int kv, f32x4 v) const {
;     ...
;             if (tw >= 0) {
;                 const size_t base = g == 0 ? O2 : (g == 1 ? O3 : O4);
;                 *(f32x4*)(out + base + ((((size_t)l * NB + b) * win + tw) * 2 + kv) * 256 + hs * 64 + dd) = v;
;             }
.LBB0_248:
	v_lshlrev_b32_e32 v168, 2, v142
	v_mov_b32_e32 v169, v2
	v_lshl_add_u64 v[168:169], v[182:183], 0, v[168:169]
	v_lshlrev_b32_e32 v182, 2, v144
	v_mov_b32_e32 v183, v2
	v_lshl_add_u64 v[168:169], v[168:169], 0, v[182:183]
	global_store_dwordx4 v[168:169], v[136:139], off offset:1024 sc1 nt

;     __device__ __forceinline__ void kvout(int row, int c, int kv, f32x4 v) const {
;     ...
;             if (tw >= 0) {
;                 const size_t base = g == 0 ? O2 : (g == 1 ? O3 : O4);
;                 *(f32x4*)(out + base + ((((size_t)l * NB + b) * win + tw) * 2 + kv) * 256 + hs * 64 + dd) = v;
;             }
.LBB0_260:
	v_lshlrev_b32_e32 v168, 2, v142
	v_mov_b32_e32 v169, v2
	v_lshl_add_u64 v[168:169], v[182:183], 0, v[168:169]
	v_lshlrev_b32_e32 v182, 2, v144
	v_mov_b32_e32 v183, v2
	v_lshl_add_u64 v[168:169], v[168:169], 0, v[182:183]
	global_store_dwordx4 v[168:169], v[136:139], off sc1 nt

;     __device__ __forceinline__ void kvout(int row, int c, int kv, f32x4 v) const {
;     ...
;             if (tw >= 0) {
;                 const size_t base = g == 0 ? O2 : (g == 1 ? O3 : O4);
;                 *(f32x4*)(out + base + ((((size_t)l * NB + b) * win + tw) * 2 + kv) * 256 + hs * 64 + dd) = v;
;             }
.LBB0_274:
	v_lshlrev_b32_e32 v138, 2, v142
	v_mov_b32_e32 v139, v2
	v_lshl_add_u64 v[136:137], v[136:137], 0, v[138:139]
	v_lshlrev_b32_e32 v138, 2, v144
	v_lshl_add_u64 v[136:137], v[136:137], 0, v[138:139]
	global_store_dwordx4 v[136:137], v[132:135], off offset:1024 sc1 nt

;     __device__ __forceinline__ void kvout(int row, int c, int kv, f32x4 v) const {
;     ...
;             if (tw >= 0) {
;                 const size_t base = g == 0 ? O2 : (g == 1 ? O3 : O4);
;                 *(f32x4*)(out + base + ((((size_t)l * NB + b) * win + tw) * 2 + kv) * 256 + hs * 64 + dd) = v;
;             }
.LBB0_286:
	v_lshlrev_b32_e32 v138, 2, v142
	v_mov_b32_e32 v139, v2
	v_lshl_add_u64 v[136:137], v[136:137], 0, v[138:139]
	v_lshlrev_b32_e32 v138, 2, v144
	v_lshl_add_u64 v[136:137], v[136:137], 0, v[138:139]
	global_store_dwordx4 v[136:137], v[132:135], off sc1 nt

;     __device__ __forceinline__ void kvout(int row, int c, int kv, f32x4 v) const {
;     ...
;             if (tw >= 0) {
;                 const size_t base = g == 0 ? O2 : (g == 1 ? O3 : O4);
;                 *(f32x4*)(out + base + ((((size_t)l * NB + b) * win + tw) * 2 + kv) * 256 + hs * 64 + dd) = v;
;             }
.LBB0_300:
	v_lshlrev_b32_e32 v134, 2, v142
	v_mov_b32_e32 v135, v2
	v_lshl_add_u64 v[132:133], v[132:133], 0, v[134:135]
	v_lshlrev_b32_e32 v134, 2, v144
	v_lshl_add_u64 v[132:133], v[132:133], 0, v[134:135]
	global_store_dwordx4 v[132:133], v[128:131], off offset:1024 sc1 nt

;     __device__ __forceinline__ void kvout(int row, int c, int kv, f32x4 v) const {
;     ...
;             if (tw >= 0) {
;                 const size_t base = g == 0 ? O2 : (g == 1 ? O3 : O4);
;                 *(f32x4*)(out + base + ((((size_t)l * NB + b) * win + tw) * 2 + kv) * 256 + hs * 64 + dd) = v;
;             }
.LBB0_312:
	v_lshlrev_b32_e32 v134, 2, v142
	v_mov_b32_e32 v135, v2
	v_lshl_add_u64 v[132:133], v[132:133], 0, v[134:135]
	v_lshlrev_b32_e32 v134, 2, v144
	v_lshl_add_u64 v[132:133], v[132:133], 0, v[134:135]
	global_store_dwordx4 v[132:133], v[128:131], off sc1 nt

;     __device__ __forceinline__ void kvout(int row, int c, int kv, f32x4 v) const {
;     ...
;             if (tw >= 0) {
;                 const size_t base = g == 0 ? O2 : (g == 1 ? O3 : O4);
;                 *(f32x4*)(out + base + ((((size_t)l * NB + b) * win + tw) * 2 + kv) * 256 + hs * 64 + dd) = v;
;             }
.LBB0_326:
	v_lshlrev_b32_e32 v130, 2, v142
	v_mov_b32_e32 v131, v2
	v_lshl_add_u64 v[128:129], v[128:129], 0, v[130:131]
	v_lshlrev_b32_e32 v130, 2, v144
	v_lshl_add_u64 v[128:129], v[128:129], 0, v[130:131]
	global_store_dwordx4 v[128:129], v[124:127], off offset:1024 sc1 nt

;     __device__ __forceinline__ void kvout(int row, int c, int kv, f32x4 v) const {
;     ...
;             if (tw >= 0) {
;                 const size_t base = g == 0 ? O2 : (g == 1 ? O3 : O4);
;                 *(f32x4*)(out + base + ((((size_t)l * NB + b) * win + tw) * 2 + kv) * 256 + hs * 64 + dd) = v;
;             }
.LBB0_338:
	v_lshlrev_b32_e32 v130, 2, v142
	v_mov_b32_e32 v131, v2
	v_lshl_add_u64 v[128:129], v[128:129], 0, v[130:131]
	v_lshlrev_b32_e32 v130, 2, v144
	v_lshl_add_u64 v[128:129], v[128:129], 0, v[130:131]
	global_store_dwordx4 v[128:129], v[124:127], off sc1 nt

;     __device__ __forceinline__ void kvout(int row, int c, int kv, f32x4 v) const {
;     ...
;             if (tw >= 0) {
;                 const size_t base = g == 0 ? O2 : (g == 1 ? O3 : O4);
;                 *(f32x4*)(out + base + ((((size_t)l * NB + b) * win + tw) * 2 + kv) * 256 + hs * 64 + dd) = v;
;             }
.LBB0_352:
	v_lshlrev_b32_e32 v126, 2, v142
	v_mov_b32_e32 v127, v2
	v_lshl_add_u64 v[124:125], v[124:125], 0, v[126:127]
	v_lshlrev_b32_e32 v126, 2, v144
	v_lshl_add_u64 v[124:125], v[124:125], 0, v[126:127]
	global_store_dwordx4 v[124:125], v[112:115], off offset:1024 sc1 nt

;     __device__ __forceinline__ void kvout(int row, int c, int kv, f32x4 v) const {
;     ...
;             if (tw >= 0) {
;                 const size_t base = g == 0 ? O2 : (g == 1 ? O3 : O4);
;                 *(f32x4*)(out + base + ((((size_t)l * NB + b) * win + tw) * 2 + kv) * 256 + hs * 64 + dd) = v;
;             }
.LBB0_364:
	v_lshlrev_b32_e32 v126, 2, v142
	v_mov_b32_e32 v127, v2
	v_lshl_add_u64 v[124:125], v[124:125], 0, v[126:127]
	v_lshlrev_b32_e32 v126, 2, v144
	v_lshl_add_u64 v[124:125], v[124:125], 0, v[126:127]
	global_store_dwordx4 v[124:125], v[112:115], off sc1 nt

;     __device__ __forceinline__ void kvout(int row, int c, int kv, f32x4 v) const {
;     ...
;             if (tw >= 0) {
;                 const size_t base = g == 0 ? O2 : (g == 1 ? O3 : O4);
;                 *(f32x4*)(out + base + ((((size_t)l * NB + b) * win + tw) * 2 + kv) * 256 + hs * 64 + dd) = v;
;             }
.LBB0_378:
	v_lshlrev_b32_e32 v114, 2, v142
	v_mov_b32_e32 v115, v2
	v_lshl_add_u64 v[112:113], v[112:113], 0, v[114:115]
	v_lshlrev_b32_e32 v114, 2, v144
	v_lshl_add_u64 v[112:113], v[112:113], 0, v[114:115]
	global_store_dwordx4 v[112:113], v[108:111], off offset:1024 sc1 nt

;     __device__ __forceinline__ void kvout(int row, int c, int kv, f32x4 v) const {
;     ...
;             if (tw >= 0) {
;                 const size_t base = g == 0 ? O2 : (g == 1 ? O3 : O4);
;                 *(f32x4*)(out + base + ((((size_t)l * NB + b) * win + tw) * 2 + kv) * 256 + hs * 64 + dd) = v;
;             }
.LBB0_390:
	v_lshlrev_b32_e32 v114, 2, v142
	v_mov_b32_e32 v115, v2
	v_lshl_add_u64 v[112:113], v[112:113], 0, v[114:115]
	v_lshlrev_b32_e32 v114, 2, v144
	v_lshl_add_u64 v[112:113], v[112:113], 0, v[114:115]
	global_store_dwordx4 v[112:113], v[108:111], off sc1 nt

;     __device__ __forceinline__ void kvout(int row, int c, int kv, f32x4 v) const {
;     ...
;             if (tw >= 0) {
;                 const size_t base = g == 0 ? O2 : (g == 1 ? O3 : O4);
;                 *(f32x4*)(out + base + ((((size_t)l * NB + b) * win + tw) * 2 + kv) * 256 + hs * 64 + dd) = v;
;             }
.LBB0_404:
	v_lshlrev_b32_e32 v110, 2, v142
	v_mov_b32_e32 v111, v2
	v_lshl_add_u64 v[108:109], v[108:109], 0, v[110:111]
	v_lshlrev_b32_e32 v110, 2, v144
	v_lshl_add_u64 v[108:109], v[108:109], 0, v[110:111]
	global_store_dwordx4 v[108:109], v[104:107], off offset:1024 sc1 nt

;     __device__ __forceinline__ void kvout(int row, int c, int kv, f32x4 v) const {
;     ...
;             if (tw >= 0) {
;                 const size_t base = g == 0 ? O2 : (g == 1 ? O3 : O4);
;                 *(f32x4*)(out + base + ((((size_t)l * NB + b) * win + tw) * 2 + kv) * 256 + hs * 64 + dd) = v;
;             }
.LBB0_416:
	v_lshlrev_b32_e32 v110, 2, v142
	v_mov_b32_e32 v111, v2
	v_lshl_add_u64 v[108:109], v[108:109], 0, v[110:111]
	v_lshlrev_b32_e32 v110, 2, v144
	v_lshl_add_u64 v[108:109], v[108:109], 0, v[110:111]
	global_store_dwordx4 v[108:109], v[104:107], off sc1 nt

;     __device__ __forceinline__ void kvout(int row, int c, int kv, f32x4 v) const {
;     ...
;             if (tw >= 0) {
;                 const size_t base = g == 0 ? O2 : (g == 1 ? O3 : O4);
;                 *(f32x4*)(out + base + ((((size_t)l * NB + b) * win + tw) * 2 + kv) * 256 + hs * 64 + dd) = v;
;             }
.LBB0_430:
	v_lshlrev_b32_e32 v106, 2, v142
	v_mov_b32_e32 v107, v2
	v_lshl_add_u64 v[104:105], v[104:105], 0, v[106:107]
	v_lshlrev_b32_e32 v106, 2, v144
	v_lshl_add_u64 v[104:105], v[104:105], 0, v[106:107]
	global_store_dwordx4 v[104:105], v[100:103], off offset:1024 sc1 nt

;     __device__ __forceinline__ void kvout(int row, int c, int kv, f32x4 v) const {
;     ...
;             if (tw >= 0) {
;                 const size_t base = g == 0 ? O2 : (g == 1 ? O3 : O4);
;                 *(f32x4*)(out + base + ((((size_t)l * NB + b) * win + tw) * 2 + kv) * 256 + hs * 64 + dd) = v;
;             }
.LBB0_442:
	v_lshlrev_b32_e32 v106, 2, v142
	v_mov_b32_e32 v107, v2
	v_lshl_add_u64 v[104:105], v[104:105], 0, v[106:107]
	v_lshlrev_b32_e32 v106, 2, v144
	v_lshl_add_u64 v[104:105], v[104:105], 0, v[106:107]
	global_store_dwordx4 v[104:105], v[100:103], off sc1 nt

;     __device__ __forceinline__ void kvout(int row, int c, int kv, f32x4 v) const {
;     ...
;             if (tw >= 0) {
;                 const size_t base = g == 0 ? O2 : (g == 1 ? O3 : O4);
;                 *(f32x4*)(out + base + ((((size_t)l * NB + b) * win + tw) * 2 + kv) * 256 + hs * 64 + dd) = v;
;             }
.LBB0_458:
	v_lshlrev_b32_e32 v168, 2, v111
	v_mov_b32_e32 v169, v2
	v_lshl_add_u64 v[168:169], v[212:213], 0, v[168:169]
	v_lshlrev_b32_e32 v212, 2, v3
	v_mov_b32_e32 v213, v2
	v_lshl_add_u64 v[168:169], v[168:169], 0, v[212:213]
	global_store_dwordx4 v[168:169], v[96:99], off offset:1024 sc1 nt

;     __device__ __forceinline__ void kvout(int row, int c, int kv, f32x4 v) const {
;     ...
;             if (tw >= 0) {
;                 const size_t base = g == 0 ? O2 : (g == 1 ? O3 : O4);
;                 *(f32x4*)(out + base + ((((size_t)l * NB + b) * win + tw) * 2 + kv) * 256 + hs * 64 + dd) = v;
;             }
.LBB0_470:
	v_lshlrev_b32_e32 v168, 2, v111
	v_mov_b32_e32 v169, v2
	v_lshl_add_u64 v[168:169], v[212:213], 0, v[168:169]
	v_lshlrev_b32_e32 v212, 2, v3
	v_mov_b32_e32 v213, v2
	v_lshl_add_u64 v[168:169], v[168:169], 0, v[212:213]
	global_store_dwordx4 v[168:169], v[96:99], off sc1 nt

;     __device__ __forceinline__ void kvout(int row, int c, int kv, f32x4 v) const {
;     ...
;             if (tw >= 0) {
;                 const size_t base = g == 0 ? O2 : (g == 1 ? O3 : O4);
;                 *(f32x4*)(out + base + ((((size_t)l * NB + b) * win + tw) * 2 + kv) * 256 + hs * 64 + dd) = v;
;             }
.LBB0_484:
	v_lshlrev_b32_e32 v168, 2, v111
	v_mov_b32_e32 v169, v2
	v_lshl_add_u64 v[98:99], v[98:99], 0, v[168:169]
	v_lshlrev_b32_e32 v168, 2, v3
	v_lshl_add_u64 v[98:99], v[98:99], 0, v[168:169]
	global_store_dwordx4 v[98:99], v[92:95], off offset:1024 sc1 nt

;     __device__ __forceinline__ void kvout(int row, int c, int kv, f32x4 v) const {
;     ...
;             if (tw >= 0) {
;                 const size_t base = g == 0 ? O2 : (g == 1 ? O3 : O4);
;                 *(f32x4*)(out + base + ((((size_t)l * NB + b) * win + tw) * 2 + kv) * 256 + hs * 64 + dd) = v;
;             }
.LBB0_496:
	v_lshlrev_b32_e32 v168, 2, v111
	v_mov_b32_e32 v169, v2
	v_lshl_add_u64 v[98:99], v[98:99], 0, v[168:169]
	v_lshlrev_b32_e32 v168, 2, v3
	v_lshl_add_u64 v[98:99], v[98:99], 0, v[168:169]
	global_store_dwordx4 v[98:99], v[92:95], off sc1 nt

;     __device__ __forceinline__ void kvout(int row, int c, int kv, f32x4 v) const {
;     ...
;             if (tw >= 0) {
;                 const size_t base = g == 0 ? O2 : (g == 1 ? O3 : O4);
;                 *(f32x4*)(out + base + ((((size_t)l * NB + b) * win + tw) * 2 + kv) * 256 + hs * 64 + dd) = v;
;             }
.LBB0_510:
	v_lshlrev_b32_e32 v98, 2, v111
	v_mov_b32_e32 v99, v2
	v_lshl_add_u64 v[94:95], v[94:95], 0, v[98:99]
	v_lshlrev_b32_e32 v98, 2, v3
	v_lshl_add_u64 v[94:95], v[94:95], 0, v[98:99]
	global_store_dwordx4 v[94:95], v[88:91], off offset:1024 sc1 nt

;     __device__ __forceinline__ void kvout(int row, int c, int kv, f32x4 v) const {
;     ...
;             if (tw >= 0) {
;                 const size_t base = g == 0 ? O2 : (g == 1 ? O3 : O4);
;                 *(f32x4*)(out + base + ((((size_t)l * NB + b) * win + tw) * 2 + kv) * 256 + hs * 64 + dd) = v;
;             }
.LBB0_522:
	v_lshlrev_b32_e32 v98, 2, v111
	v_mov_b32_e32 v99, v2
	v_lshl_add_u64 v[94:95], v[94:95], 0, v[98:99]
	v_lshlrev_b32_e32 v98, 2, v3
	v_lshl_add_u64 v[94:95], v[94:95], 0, v[98:99]
	global_store_dwordx4 v[94:95], v[88:91], off sc1 nt

;     __device__ __forceinline__ void kvout(int row, int c, int kv, f32x4 v) const {
;     ...
;             if (tw >= 0) {
;                 const size_t base = g == 0 ? O2 : (g == 1 ? O3 : O4);
;                 *(f32x4*)(out + base + ((((size_t)l * NB + b) * win + tw) * 2 + kv) * 256 + hs * 64 + dd) = v;
;             }
.LBB0_536:
	v_lshlrev_b32_e32 v94, 2, v111
	v_mov_b32_e32 v95, v2
	v_lshl_add_u64 v[90:91], v[90:91], 0, v[94:95]
	v_lshlrev_b32_e32 v94, 2, v3
	v_lshl_add_u64 v[90:91], v[90:91], 0, v[94:95]
	global_store_dwordx4 v[90:91], v[84:87], off offset:1024 sc1 nt

;     __device__ __forceinline__ void kvout(int row, int c, int kv, f32x4 v) const {
;     ...
;             if (tw >= 0) {
;                 const size_t base = g == 0 ? O2 : (g == 1 ? O3 : O4);
;                 *(f32x4*)(out + base + ((((size_t)l * NB + b) * win + tw) * 2 + kv) * 256 + hs * 64 + dd) = v;
;             }
.LBB0_548:
	v_lshlrev_b32_e32 v94, 2, v111
	v_mov_b32_e32 v95, v2
	v_lshl_add_u64 v[90:91], v[90:91], 0, v[94:95]
	v_lshlrev_b32_e32 v94, 2, v3
	v_lshl_add_u64 v[90:91], v[90:91], 0, v[94:95]
	global_store_dwordx4 v[90:91], v[84:87], off sc1 nt

;     __device__ __forceinline__ void kvout(int row, int c, int kv, f32x4 v) const {
;     ...
;             if (tw >= 0) {
;                 const size_t base = g == 0 ? O2 : (g == 1 ? O3 : O4);
;                 *(f32x4*)(out + base + ((((size_t)l * NB + b) * win + tw) * 2 + kv) * 256 + hs * 64 + dd) = v;
;             }
.LBB0_562:
	v_lshlrev_b32_e32 v90, 2, v111
	v_mov_b32_e32 v91, v2
	v_lshl_add_u64 v[86:87], v[86:87], 0, v[90:91]
	v_lshlrev_b32_e32 v90, 2, v3
	v_lshl_add_u64 v[86:87], v[86:87], 0, v[90:91]
	global_store_dwordx4 v[86:87], v[80:83], off offset:1024 sc1 nt

;     __device__ __forceinline__ void kvout(int row, int c, int kv, f32x4 v) const {
;     ...
;             if (tw >= 0) {
;                 const size_t base = g == 0 ? O2 : (g == 1 ? O3 : O4);
;                 *(f32x4*)(out + base + ((((size_t)l * NB + b) * win + tw) * 2 + kv) * 256 + hs * 64 + dd) = v;
;             }
.LBB0_574:
	v_lshlrev_b32_e32 v90, 2, v111
	v_mov_b32_e32 v91, v2
	v_lshl_add_u64 v[86:87], v[86:87], 0, v[90:91]
	v_lshlrev_b32_e32 v90, 2, v3
	v_lshl_add_u64 v[86:87], v[86:87], 0, v[90:91]
	global_store_dwordx4 v[86:87], v[80:83], off sc1 nt

;     __device__ __forceinline__ void kvout(int row, int c, int kv, f32x4 v) const {
;     ...
;             if (tw >= 0) {
;                 const size_t base = g == 0 ? O2 : (g == 1 ? O3 : O4);
;                 *(f32x4*)(out + base + ((((size_t)l * NB + b) * win + tw) * 2 + kv) * 256 + hs * 64 + dd) = v;
;             }
.LBB0_588:
	v_lshlrev_b32_e32 v86, 2, v111
	v_mov_b32_e32 v87, v2
	v_lshl_add_u64 v[82:83], v[82:83], 0, v[86:87]
	v_lshlrev_b32_e32 v86, 2, v3
	v_lshl_add_u64 v[82:83], v[82:83], 0, v[86:87]
	global_store_dwordx4 v[82:83], v[76:79], off offset:1024 sc1 nt

;     __device__ __forceinline__ void kvout(int row, int c, int kv, f32x4 v) const {
;     ...
;             if (tw >= 0) {
;                 const size_t base = g == 0 ? O2 : (g == 1 ? O3 : O4);
;                 *(f32x4*)(out + base + ((((size_t)l * NB + b) * win + tw) * 2 + kv) * 256 + hs * 64 + dd) = v;
;             }
.LBB0_600:
	v_lshlrev_b32_e32 v86, 2, v111
	v_mov_b32_e32 v87, v2
	v_lshl_add_u64 v[82:83], v[82:83], 0, v[86:87]
	v_lshlrev_b32_e32 v86, 2, v3
	v_lshl_add_u64 v[82:83], v[82:83], 0, v[86:87]
	global_store_dwordx4 v[82:83], v[76:79], off sc1 nt

;     __device__ __forceinline__ void kvout(int row, int c, int kv, f32x4 v) const {
;     ...
;             if (tw >= 0) {
;                 const size_t base = g == 0 ? O2 : (g == 1 ? O3 : O4);
;                 *(f32x4*)(out + base + ((((size_t)l * NB + b) * win + tw) * 2 + kv) * 256 + hs * 64 + dd) = v;
;             }
.LBB0_614:
	v_lshlrev_b32_e32 v82, 2, v111
	v_mov_b32_e32 v83, v2
	v_lshl_add_u64 v[76:77], v[76:77], 0, v[82:83]
	v_lshlrev_b32_e32 v82, 2, v3
	v_lshl_add_u64 v[76:77], v[76:77], 0, v[82:83]
	global_store_dwordx4 v[76:77], v[72:75], off offset:1024 sc1 nt

;     __device__ __forceinline__ void kvout(int row, int c, int kv, f32x4 v) const {
;     ...
;             if (tw >= 0) {
;                 const size_t base = g == 0 ? O2 : (g == 1 ? O3 : O4);
;                 *(f32x4*)(out + base + ((((size_t)l * NB + b) * win + tw) * 2 + kv) * 256 + hs * 64 + dd) = v;
;             }
.LBB0_626:
	v_lshlrev_b32_e32 v82, 2, v111
	v_mov_b32_e32 v83, v2
	v_lshl_add_u64 v[76:77], v[76:77], 0, v[82:83]
	v_lshlrev_b32_e32 v82, 2, v3
	v_lshl_add_u64 v[76:77], v[76:77], 0, v[82:83]
	global_store_dwordx4 v[76:77], v[72:75], off sc1 nt

;     __device__ __forceinline__ void kvout(int row, int c, int kv, f32x4 v) const {
;     ...
;             if (tw >= 0) {
;                 const size_t base = g == 0 ? O2 : (g == 1 ? O3 : O4);
;                 *(f32x4*)(out + base + ((((size_t)l * NB + b) * win + tw) * 2 + kv) * 256 + hs * 64 + dd) = v;
;             }
.LBB0_640:
	v_lshlrev_b32_e32 v74, 2, v111
	v_mov_b32_e32 v75, v2
	v_lshl_add_u64 v[72:73], v[72:73], 0, v[74:75]
	v_lshlrev_b32_e32 v74, 2, v3
	v_lshl_add_u64 v[72:73], v[72:73], 0, v[74:75]
	global_store_dwordx4 v[72:73], v[68:71], off offset:1024 sc1 nt

;     __device__ __forceinline__ void kvout(int row, int c, int kv, f32x4 v) const {
;     ...
;             if (tw >= 0) {
;                 const size_t base = g == 0 ? O2 : (g == 1 ? O3 : O4);
;                 *(f32x4*)(out + base + ((((size_t)l * NB + b) * win + tw) * 2 + kv) * 256 + hs * 64 + dd) = v;
;             }
.LBB0_652:
	v_lshlrev_b32_e32 v74, 2, v111
	v_mov_b32_e32 v75, v2
	v_lshl_add_u64 v[72:73], v[72:73], 0, v[74:75]
	v_lshlrev_b32_e32 v74, 2, v3
	v_lshl_add_u64 v[72:73], v[72:73], 0, v[74:75]
	global_store_dwordx4 v[72:73], v[68:71], off sc1 nt

;     __device__ __forceinline__ void kvout(int row, int c, int kv, f32x4 v) const {
;     ...
;             if (tw >= 0) {
;                 const size_t base = g == 0 ? O2 : (g == 1 ? O3 : O4);
;                 *(f32x4*)(out + base + ((((size_t)l * NB + b) * win + tw) * 2 + kv) * 256 + hs * 64 + dd) = v;
;             }
.LBB0_668:
	v_lshlrev_b32_e32 v98, 2, v3
	v_mov_b32_e32 v99, v2
	v_lshl_add_u64 v[94:95], v[94:95], 0, v[98:99]
	v_lshlrev_b32_e32 v98, 2, v144
	v_lshl_add_u64 v[94:95], v[94:95], 0, v[98:99]
	global_store_dwordx4 v[94:95], v[64:67], off offset:1024 sc1 nt

;     __device__ __forceinline__ void kvout(int row, int c, int kv, f32x4 v) const {
;     ...
;             if (tw >= 0) {
;                 const size_t base = g == 0 ? O2 : (g == 1 ? O3 : O4);
;                 *(f32x4*)(out + base + ((((size_t)l * NB + b) * win + tw) * 2 + kv) * 256 + hs * 64 + dd) = v;
;             }
.LBB0_680:
	v_lshlrev_b32_e32 v98, 2, v3
	v_mov_b32_e32 v99, v2
	v_lshl_add_u64 v[94:95], v[94:95], 0, v[98:99]
	v_lshlrev_b32_e32 v98, 2, v144
	v_lshl_add_u64 v[94:95], v[94:95], 0, v[98:99]
	global_store_dwordx4 v[94:95], v[64:67], off sc1 nt

;     __device__ __forceinline__ void kvout(int row, int c, int kv, f32x4 v) const {
;     ...
;             if (tw >= 0) {
;                 const size_t base = g == 0 ? O2 : (g == 1 ? O3 : O4);
;                 *(f32x4*)(out + base + ((((size_t)l * NB + b) * win + tw) * 2 + kv) * 256 + hs * 64 + dd) = v;
;             }
.LBB0_694:
	v_lshlrev_b32_e32 v66, 2, v3
	v_mov_b32_e32 v67, v2
	v_lshl_add_u64 v[64:65], v[64:65], 0, v[66:67]
	v_lshlrev_b32_e32 v66, 2, v144
	v_lshl_add_u64 v[64:65], v[64:65], 0, v[66:67]
	global_store_dwordx4 v[64:65], v[60:63], off offset:1024 sc1 nt

;     __device__ __forceinline__ void kvout(int row, int c, int kv, f32x4 v) const {
;     ...
;             if (tw >= 0) {
;                 const size_t base = g == 0 ? O2 : (g == 1 ? O3 : O4);
;                 *(f32x4*)(out + base + ((((size_t)l * NB + b) * win + tw) * 2 + kv) * 256 + hs * 64 + dd) = v;
;             }
.LBB0_706:
	v_lshlrev_b32_e32 v66, 2, v3
	v_mov_b32_e32 v67, v2
	v_lshl_add_u64 v[64:65], v[64:65], 0, v[66:67]
	v_lshlrev_b32_e32 v66, 2, v144
	v_lshl_add_u64 v[64:65], v[64:65], 0, v[66:67]
	global_store_dwordx4 v[64:65], v[60:63], off sc1 nt

;     __device__ __forceinline__ void kvout(int row, int c, int kv, f32x4 v) const {
;     ...
;             if (tw >= 0) {
;                 const size_t base = g == 0 ? O2 : (g == 1 ? O3 : O4);
;                 *(f32x4*)(out + base + ((((size_t)l * NB + b) * win + tw) * 2 + kv) * 256 + hs * 64 + dd) = v;
;             }
.LBB0_720:
	v_lshlrev_b32_e32 v62, 2, v3
	v_mov_b32_e32 v63, v2
	v_lshl_add_u64 v[60:61], v[60:61], 0, v[62:63]
	v_lshlrev_b32_e32 v62, 2, v144
	v_lshl_add_u64 v[60:61], v[60:61], 0, v[62:63]
	global_store_dwordx4 v[60:61], v[56:59], off offset:1024 sc1 nt

;     __device__ __forceinline__ void kvout(int row, int c, int kv, f32x4 v) const {
;     ...
;             if (tw >= 0) {
;                 const size_t base = g == 0 ? O2 : (g == 1 ? O3 : O4);
;                 *(f32x4*)(out + base + ((((size_t)l * NB + b) * win + tw) * 2 + kv) * 256 + hs * 64 + dd) = v;
;             }
.LBB0_732:
	v_lshlrev_b32_e32 v62, 2, v3
	v_mov_b32_e32 v63, v2
	v_lshl_add_u64 v[60:61], v[60:61], 0, v[62:63]
	v_lshlrev_b32_e32 v62, 2, v144
	v_lshl_add_u64 v[60:61], v[60:61], 0, v[62:63]
	global_store_dwordx4 v[60:61], v[56:59], off sc1 nt

;     __device__ __forceinline__ void kvout(int row, int c, int kv, f32x4 v) const {
;     ...
;             if (tw >= 0) {
;                 const size_t base = g == 0 ? O2 : (g == 1 ? O3 : O4);
;                 *(f32x4*)(out + base + ((((size_t)l * NB + b) * win + tw) * 2 + kv) * 256 + hs * 64 + dd) = v;
;             }
.LBB0_746:
	v_lshlrev_b32_e32 v58, 2, v3
	v_mov_b32_e32 v59, v2
	v_lshl_add_u64 v[56:57], v[56:57], 0, v[58:59]
	v_lshlrev_b32_e32 v58, 2, v144
	v_lshl_add_u64 v[56:57], v[56:57], 0, v[58:59]
	global_store_dwordx4 v[56:57], v[52:55], off offset:1024 sc1 nt

;     __device__ __forceinline__ void kvout(int row, int c, int kv, f32x4 v) const {
;     ...
;             if (tw >= 0) {
;                 const size_t base = g == 0 ? O2 : (g == 1 ? O3 : O4);
;                 *(f32x4*)(out + base + ((((size_t)l * NB + b) * win + tw) * 2 + kv) * 256 + hs * 64 + dd) = v;
;             }
.LBB0_758:
	v_lshlrev_b32_e32 v58, 2, v3
	v_mov_b32_e32 v59, v2
	v_lshl_add_u64 v[56:57], v[56:57], 0, v[58:59]
	v_lshlrev_b32_e32 v58, 2, v144
	v_lshl_add_u64 v[56:57], v[56:57], 0, v[58:59]
	global_store_dwordx4 v[56:57], v[52:55], off sc1 nt

;     __device__ __forceinline__ void kvout(int row, int c, int kv, f32x4 v) const {
;     ...
;             if (tw >= 0) {
;                 const size_t base = g == 0 ? O2 : (g == 1 ? O3 : O4);
;                 *(f32x4*)(out + base + ((((size_t)l * NB + b) * win + tw) * 2 + kv) * 256 + hs * 64 + dd) = v;
;             }
.LBB0_772:
	v_lshlrev_b32_e32 v54, 2, v3
	v_mov_b32_e32 v55, v2
	v_lshl_add_u64 v[52:53], v[52:53], 0, v[54:55]
	v_lshlrev_b32_e32 v54, 2, v144
	v_lshl_add_u64 v[52:53], v[52:53], 0, v[54:55]
	global_store_dwordx4 v[52:53], v[48:51], off offset:1024 sc1 nt

;     __device__ __forceinline__ void kvout(int row, int c, int kv, f32x4 v) const {
;     ...
;             if (tw >= 0) {
;                 const size_t base = g == 0 ? O2 : (g == 1 ? O3 : O4);
;                 *(f32x4*)(out + base + ((((size_t)l * NB + b) * win + tw) * 2 + kv) * 256 + hs * 64 + dd) = v;
;             }
.LBB0_784:
	v_lshlrev_b32_e32 v54, 2, v3
	v_mov_b32_e32 v55, v2
	v_lshl_add_u64 v[52:53], v[52:53], 0, v[54:55]
	v_lshlrev_b32_e32 v54, 2, v144
	v_lshl_add_u64 v[52:53], v[52:53], 0, v[54:55]
	global_store_dwordx4 v[52:53], v[48:51], off sc1 nt

;     __device__ __forceinline__ void kvout(int row, int c, int kv, f32x4 v) const {
;     ...
;             if (tw >= 0) {
;                 const size_t base = g == 0 ? O2 : (g == 1 ? O3 : O4);
;                 *(f32x4*)(out + base + ((((size_t)l * NB + b) * win + tw) * 2 + kv) * 256 + hs * 64 + dd) = v;
;             }
.LBB0_798:
	v_lshlrev_b32_e32 v50, 2, v3
	v_mov_b32_e32 v51, v2
	v_lshl_add_u64 v[48:49], v[48:49], 0, v[50:51]
	v_lshlrev_b32_e32 v50, 2, v144
	v_lshl_add_u64 v[48:49], v[48:49], 0, v[50:51]
	global_store_dwordx4 v[48:49], v[44:47], off offset:1024 sc1 nt

;     __device__ __forceinline__ void kvout(int row, int c, int kv, f32x4 v) const {
;     ...
;             if (tw >= 0) {
;                 const size_t base = g == 0 ? O2 : (g == 1 ? O3 : O4);
;                 *(f32x4*)(out + base + ((((size_t)l * NB + b) * win + tw) * 2 + kv) * 256 + hs * 64 + dd) = v;
;             }
.LBB0_810:
	v_lshlrev_b32_e32 v50, 2, v3
	v_mov_b32_e32 v51, v2
	v_lshl_add_u64 v[48:49], v[48:49], 0, v[50:51]
	v_lshlrev_b32_e32 v50, 2, v144
	v_lshl_add_u64 v[48:49], v[48:49], 0, v[50:51]
	global_store_dwordx4 v[48:49], v[44:47], off sc1 nt

;     __device__ __forceinline__ void kvout(int row, int c, int kv, f32x4 v) const {
;     ...
;             if (tw >= 0) {
;                 const size_t base = g == 0 ? O2 : (g == 1 ? O3 : O4);
;                 *(f32x4*)(out + base + ((((size_t)l * NB + b) * win + tw) * 2 + kv) * 256 + hs * 64 + dd) = v;
;             }
.LBB0_824:
	v_lshlrev_b32_e32 v46, 2, v3
	v_mov_b32_e32 v47, v2
	v_lshl_add_u64 v[44:45], v[44:45], 0, v[46:47]
	v_lshlrev_b32_e32 v46, 2, v144
	v_lshl_add_u64 v[44:45], v[44:45], 0, v[46:47]
	global_store_dwordx4 v[44:45], v[40:43], off offset:1024 sc1 nt

;     __device__ __forceinline__ void kvout(int row, int c, int kv, f32x4 v) const {
;     ...
;             if (tw >= 0) {
;                 const size_t base = g == 0 ? O2 : (g == 1 ? O3 : O4);
;                 *(f32x4*)(out + base + ((((size_t)l * NB + b) * win + tw) * 2 + kv) * 256 + hs * 64 + dd) = v;
;             }
.LBB0_836:
	v_lshlrev_b32_e32 v46, 2, v3
	v_mov_b32_e32 v47, v2
	v_lshl_add_u64 v[44:45], v[44:45], 0, v[46:47]
	v_lshlrev_b32_e32 v46, 2, v144
	v_lshl_add_u64 v[44:45], v[44:45], 0, v[46:47]
	global_store_dwordx4 v[44:45], v[40:43], off sc1 nt

;     __device__ __forceinline__ void kvout(int row, int c, int kv, f32x4 v) const {
;     ...
;             if (tw >= 0) {
;                 const size_t base = g == 0 ? O2 : (g == 1 ? O3 : O4);
;                 *(f32x4*)(out + base + ((((size_t)l * NB + b) * win + tw) * 2 + kv) * 256 + hs * 64 + dd) = v;
;             }
.LBB0_850:
	v_lshlrev_b32_e32 v42, 2, v3
	v_mov_b32_e32 v43, v2
	v_lshl_add_u64 v[40:41], v[40:41], 0, v[42:43]
	v_lshlrev_b32_e32 v42, 2, v144
	v_lshl_add_u64 v[40:41], v[40:41], 0, v[42:43]
	global_store_dwordx4 v[40:41], v[36:39], off offset:1024 sc1 nt

;     __device__ __forceinline__ void kvout(int row, int c, int kv, f32x4 v) const {
;     ...
;             if (tw >= 0) {
;                 const size_t base = g == 0 ? O2 : (g == 1 ? O3 : O4);
;                 *(f32x4*)(out + base + ((((size_t)l * NB + b) * win + tw) * 2 + kv) * 256 + hs * 64 + dd) = v;
;             }
.LBB0_862:
	v_lshlrev_b32_e32 v42, 2, v3
	v_mov_b32_e32 v43, v2
	v_lshl_add_u64 v[40:41], v[40:41], 0, v[42:43]
	v_lshlrev_b32_e32 v42, 2, v144
	v_lshl_add_u64 v[40:41], v[40:41], 0, v[42:43]
	global_store_dwordx4 v[40:41], v[36:39], off sc1 nt

;     __device__ __forceinline__ void kvout(int row, int c, int kv, f32x4 v) const {
;     ...
;             if (tw >= 0) {
;                 const size_t base = g == 0 ? O2 : (g == 1 ? O3 : O4);
;                 *(f32x4*)(out + base + ((((size_t)l * NB + b) * win + tw) * 2 + kv) * 256 + hs * 64 + dd) = v;
;             }
.LBB0_878:
	v_lshlrev_b32_e32 v52, 2, v54
	v_mov_b32_e32 v53, v2
	v_lshl_add_u64 v[50:51], v[50:51], 0, v[52:53]
	v_lshlrev_b32_e32 v52, 2, v3
	v_lshl_add_u64 v[50:51], v[50:51], 0, v[52:53]
	global_store_dwordx4 v[50:51], v[32:35], off offset:1024 sc1 nt

;     __device__ __forceinline__ void kvout(int row, int c, int kv, f32x4 v) const {
;     ...
;             if (tw >= 0) {
;                 const size_t base = g == 0 ? O2 : (g == 1 ? O3 : O4);
;                 *(f32x4*)(out + base + ((((size_t)l * NB + b) * win + tw) * 2 + kv) * 256 + hs * 64 + dd) = v;
;             }
.LBB0_890:
	v_lshlrev_b32_e32 v52, 2, v54
	v_mov_b32_e32 v53, v2
	v_lshl_add_u64 v[50:51], v[50:51], 0, v[52:53]
	v_lshlrev_b32_e32 v52, 2, v3
	v_lshl_add_u64 v[50:51], v[50:51], 0, v[52:53]
	global_store_dwordx4 v[50:51], v[32:35], off sc1 nt

;     __device__ __forceinline__ void kvout(int row, int c, int kv, f32x4 v) const {
;     ...
;             if (tw >= 0) {
;                 const size_t base = g == 0 ? O2 : (g == 1 ? O3 : O4);
;                 *(f32x4*)(out + base + ((((size_t)l * NB + b) * win + tw) * 2 + kv) * 256 + hs * 64 + dd) = v;
;             }
.LBB0_904:
	v_lshlrev_b32_e32 v34, 2, v54
	v_mov_b32_e32 v35, v2
	v_lshl_add_u64 v[32:33], v[32:33], 0, v[34:35]
	v_lshlrev_b32_e32 v34, 2, v3
	v_lshl_add_u64 v[32:33], v[32:33], 0, v[34:35]
	global_store_dwordx4 v[32:33], v[28:31], off offset:1024 sc1 nt

;     __device__ __forceinline__ void kvout(int row, int c, int kv, f32x4 v) const {
;     ...
;             if (tw >= 0) {
;                 const size_t base = g == 0 ? O2 : (g == 1 ? O3 : O4);
;                 *(f32x4*)(out + base + ((((size_t)l * NB + b) * win + tw) * 2 + kv) * 256 + hs * 64 + dd) = v;
;             }
.LBB0_916:
	v_lshlrev_b32_e32 v34, 2, v54
	v_mov_b32_e32 v35, v2
	v_lshl_add_u64 v[32:33], v[32:33], 0, v[34:35]
	v_lshlrev_b32_e32 v34, 2, v3
	v_lshl_add_u64 v[32:33], v[32:33], 0, v[34:35]
	global_store_dwordx4 v[32:33], v[28:31], off sc1 nt

;     __device__ __forceinline__ void kvout(int row, int c, int kv, f32x4 v) const {
;     ...
;             if (tw >= 0) {
;                 const size_t base = g == 0 ? O2 : (g == 1 ? O3 : O4);
;                 *(f32x4*)(out + base + ((((size_t)l * NB + b) * win + tw) * 2 + kv) * 256 + hs * 64 + dd) = v;
;             }
.LBB0_930:
	v_lshlrev_b32_e32 v30, 2, v54
	v_mov_b32_e32 v31, v2
	v_lshl_add_u64 v[28:29], v[28:29], 0, v[30:31]
	v_lshlrev_b32_e32 v30, 2, v3
	v_lshl_add_u64 v[28:29], v[28:29], 0, v[30:31]
	global_store_dwordx4 v[28:29], v[24:27], off offset:1024 sc1 nt

;     __device__ __forceinline__ void kvout(int row, int c, int kv, f32x4 v) const {
;     ...
;             if (tw >= 0) {
;                 const size_t base = g == 0 ? O2 : (g == 1 ? O3 : O4);
;                 *(f32x4*)(out + base + ((((size_t)l * NB + b) * win + tw) * 2 + kv) * 256 + hs * 64 + dd) = v;
;             }
.LBB0_942:
	v_lshlrev_b32_e32 v30, 2, v54
	v_mov_b32_e32 v31, v2
	v_lshl_add_u64 v[28:29], v[28:29], 0, v[30:31]
	v_lshlrev_b32_e32 v30, 2, v3
	v_lshl_add_u64 v[28:29], v[28:29], 0, v[30:31]
	global_store_dwordx4 v[28:29], v[24:27], off sc1 nt

;     __device__ __forceinline__ void kvout(int row, int c, int kv, f32x4 v) const {
;     ...
;             if (tw >= 0) {
;                 const size_t base = g == 0 ? O2 : (g == 1 ? O3 : O4);
;                 *(f32x4*)(out + base + ((((size_t)l * NB + b) * win + tw) * 2 + kv) * 256 + hs * 64 + dd) = v;
;             }
.LBB0_956:
	v_lshlrev_b32_e32 v26, 2, v54
	v_mov_b32_e32 v27, v2
	v_lshl_add_u64 v[24:25], v[24:25], 0, v[26:27]
	v_lshlrev_b32_e32 v26, 2, v3
	v_lshl_add_u64 v[24:25], v[24:25], 0, v[26:27]
	global_store_dwordx4 v[24:25], v[20:23], off offset:1024 sc1 nt

;     __device__ __forceinline__ void kvout(int row, int c, int kv, f32x4 v) const {
;     ...
;             if (tw >= 0) {
;                 const size_t base = g == 0 ? O2 : (g == 1 ? O3 : O4);
;                 *(f32x4*)(out + base + ((((size_t)l * NB + b) * win + tw) * 2 + kv) * 256 + hs * 64 + dd) = v;
;             }
.LBB0_968:
	v_lshlrev_b32_e32 v26, 2, v54
	v_mov_b32_e32 v27, v2
	v_lshl_add_u64 v[24:25], v[24:25], 0, v[26:27]
	v_lshlrev_b32_e32 v26, 2, v3
	v_lshl_add_u64 v[24:25], v[24:25], 0, v[26:27]
	global_store_dwordx4 v[24:25], v[20:23], off sc1 nt

;     __device__ __forceinline__ void kvout(int row, int c, int kv, f32x4 v) const {
;         const int head = c >> 6, g = head >> 2, hs = head & 3, dd = c & 63;
;         if (row < MP) {
;             const int b = row >> 11, t = row & 2047;
;             const int win = g == 0 ? 128 : (g == 1 ? 512 : 2048);
;             const int tw = t - (2048 - win);
;             if (tw >= 0) {
;                 const size_t base = g == 0 ? O2 : (g == 1 ? O3 : O4);
;                 *(f32x4*)(out + base + ((((size_t)l * NB + b) * win + tw) * 2 + kv) * 256 + hs * 64 + dd) = v;
;             }
;         } else if (row < MR) {
;             const int r = row - MP;
;             const size_t base = g == 0 ? O6 : (g == 1 ? O7 : O8);
;             *(f32x4*)(out + base + (((size_t)l * MS + r) * 2 + kv) * 256 + hs * 64 + dd) = v;
;         }
.LBB0_982:
	v_lshlrev_b32_e32 v22, 2, v54
	v_mov_b32_e32 v23, v2
	v_lshl_add_u64 v[20:21], v[20:21], 0, v[22:23]
	v_lshlrev_b32_e32 v22, 2, v3
	v_lshl_add_u64 v[20:21], v[20:21], 0, v[22:23]
	global_store_dwordx4 v[20:21], v[16:19], off offset:1024 sc1 nt

;     __device__ __forceinline__ void kvout(int row, int c, int kv, f32x4 v) const {
;         const int head = c >> 6, g = head >> 2, hs = head & 3, dd = c & 63;
;         if (row < MP) {
;             const int b = row >> 11, t = row & 2047;
;             const int win = g == 0 ? 128 : (g == 1 ? 512 : 2048);
;             const int tw = t - (2048 - win);
;             if (tw >= 0) {
;                 const size_t base = g == 0 ? O2 : (g == 1 ? O3 : O4);
;                 *(f32x4*)(out + base + ((((size_t)l * NB + b) * win + tw) * 2 + kv) * 256 + hs * 64 + dd) = v;
;             }
;         } else if (row < MR) {
;             const int r = row - MP;
;             const size_t base = g == 0 ? O6 : (g == 1 ? O7 : O8);
;             *(f32x4*)(out + base + (((size_t)l * MS + r) * 2 + kv) * 256 + hs * 64 + dd) = v;
;         }
.LBB0_994:
	v_lshlrev_b32_e32 v22, 2, v54
	v_mov_b32_e32 v23, v2
	v_lshl_add_u64 v[20:21], v[20:21], 0, v[22:23]
	v_lshlrev_b32_e32 v22, 2, v3
	v_lshl_add_u64 v[20:21], v[20:21], 0, v[22:23]
	global_store_dwordx4 v[20:21], v[16:19], off sc1 nt

;     __device__ __forceinline__ void kvout(int row, int c, int kv, f32x4 v) const {
;         const int head = c >> 6, g = head >> 2, hs = head & 3, dd = c & 63;
;         if (row < MP) {
;             const int b = row >> 11, t = row & 2047;
;             const int win = g == 0 ? 128 : (g == 1 ? 512 : 2048);
;             const int tw = t - (2048 - win);
;             if (tw >= 0) {
;                 const size_t base = g == 0 ? O2 : (g == 1 ? O3 : O4);
;                 *(f32x4*)(out + base + ((((size_t)l * NB + b) * win + tw) * 2 + kv) * 256 + hs * 64 + dd) = v;
;             }
;         } else if (row < MR) {
;             const int r = row - MP;
;             const size_t base = g == 0 ? O6 : (g == 1 ? O7 : O8);
;             *(f32x4*)(out + base + (((size_t)l * MS + r) * 2 + kv) * 256 + hs * 64 + dd) = v;
;         }
.LBB0_1008:
	v_lshlrev_b32_e32 v18, 2, v54
	v_mov_b32_e32 v19, v2
	v_lshl_add_u64 v[16:17], v[16:17], 0, v[18:19]
	v_lshlrev_b32_e32 v18, 2, v3
	v_lshl_add_u64 v[16:17], v[16:17], 0, v[18:19]
	global_store_dwordx4 v[16:17], v[12:15], off offset:1024 sc1 nt

;     __device__ __forceinline__ void kvout(int row, int c, int kv, f32x4 v) const {
;         const int head = c >> 6, g = head >> 2, hs = head & 3, dd = c & 63;
;         if (row < MP) {
;             const int b = row >> 11, t = row & 2047;
;             const int win = g == 0 ? 128 : (g == 1 ? 512 : 2048);
;             const int tw = t - (2048 - win);
;             if (tw >= 0) {
;                 const size_t base = g == 0 ? O2 : (g == 1 ? O3 : O4);
;                 *(f32x4*)(out + base + ((((size_t)l * NB + b) * win + tw) * 2 + kv) * 256 + hs * 64 + dd) = v;
;             }
;         } else if (row < MR) {
;             const int r = row - MP;
;             const size_t base = g == 0 ? O6 : (g == 1 ? O7 : O8);
;             *(f32x4*)(out + base + (((size_t)l * MS + r) * 2 + kv) * 256 + hs * 64 + dd) = v;
;         }
.LBB0_1020:
	v_lshlrev_b32_e32 v18, 2, v54
	v_mov_b32_e32 v19, v2
	v_lshl_add_u64 v[16:17], v[16:17], 0, v[18:19]
	v_lshlrev_b32_e32 v18, 2, v3
	v_lshl_add_u64 v[16:17], v[16:17], 0, v[18:19]
	global_store_dwordx4 v[16:17], v[12:15], off sc1 nt

;     __device__ __forceinline__ void kvout(int row, int c, int kv, f32x4 v) const {
;         const int head = c >> 6, g = head >> 2, hs = head & 3, dd = c & 63;
;         if (row < MP) {
;             const int b = row >> 11, t = row & 2047;
;             const int win = g == 0 ? 128 : (g == 1 ? 512 : 2048);
;             const int tw = t - (2048 - win);
;             if (tw >= 0) {
;                 const size_t base = g == 0 ? O2 : (g == 1 ? O3 : O4);
;                 *(f32x4*)(out + base + ((((size_t)l * NB + b) * win + tw) * 2 + kv) * 256 + hs * 64 + dd) = v;
;             }
;         } else if (row < MR) {
;             const int r = row - MP;
;             const size_t base = g == 0 ? O6 : (g == 1 ? O7 : O8);
;             *(f32x4*)(out + base + (((size_t)l * MS + r) * 2 + kv) * 256 + hs * 64 + dd) = v;
;         }
.LBB0_1034:
	v_lshlrev_b32_e32 v14, 2, v54
	v_mov_b32_e32 v15, v2
	v_lshl_add_u64 v[12:13], v[12:13], 0, v[14:15]
	v_lshlrev_b32_e32 v14, 2, v3
	v_lshl_add_u64 v[12:13], v[12:13], 0, v[14:15]
	global_store_dwordx4 v[12:13], v[8:11], off offset:1024 sc1 nt

;     __device__ __forceinline__ void kvout(int row, int c, int kv, f32x4 v) const {
;         const int head = c >> 6, g = head >> 2, hs = head & 3, dd = c & 63;
;         if (row < MP) {
;             const int b = row >> 11, t = row & 2047;
;             const int win = g == 0 ? 128 : (g == 1 ? 512 : 2048);
;             const int tw = t - (2048 - win);
;             if (tw >= 0) {
;                 const size_t base = g == 0 ? O2 : (g == 1 ? O3 : O4);
;                 *(f32x4*)(out + base + ((((size_t)l * NB + b) * win + tw) * 2 + kv) * 256 + hs * 64 + dd) = v;
;             }
;         } else if (row < MR) {
;             const int r = row - MP;
;             const size_t base = g == 0 ? O6 : (g == 1 ? O7 : O8);
;             *(f32x4*)(out + base + (((size_t)l * MS + r) * 2 + kv) * 256 + hs * 64 + dd) = v;
;         }
.LBB0_1046:
	v_lshlrev_b32_e32 v14, 2, v54
	v_mov_b32_e32 v15, v2
	v_lshl_add_u64 v[12:13], v[12:13], 0, v[14:15]
	v_lshlrev_b32_e32 v14, 2, v3
	v_lshl_add_u64 v[12:13], v[12:13], 0, v[14:15]
	global_store_dwordx4 v[12:13], v[8:11], off sc1 nt

;     __device__ __forceinline__ void kvout(int row, int c, int kv, f32x4 v) const {
;         const int head = c >> 6, g = head >> 2, hs = head & 3, dd = c & 63;
;         if (row < MP) {
;             const int b = row >> 11, t = row & 2047;
;             const int win = g == 0 ? 128 : (g == 1 ? 512 : 2048);
;             const int tw = t - (2048 - win);
;             if (tw >= 0) {
;                 const size_t base = g == 0 ? O2 : (g == 1 ? O3 : O4);
;                 *(f32x4*)(out + base + ((((size_t)l * NB + b) * win + tw) * 2 + kv) * 256 + hs * 64 + dd) = v;
;             }
;         } else if (row < MR) {
;             const int r = row - MP;
;             const size_t base = g == 0 ? O6 : (g == 1 ? O7 : O8);
;             *(f32x4*)(out + base + (((size_t)l * MS + r) * 2 + kv) * 256 + hs * 64 + dd) = v;
;         }
.LBB0_1063:
	v_lshlrev_b32_e32 v10, 2, v54
	v_mov_b32_e32 v11, v2
	v_lshl_add_u64 v[8:9], v[8:9], 0, v[10:11]
	v_lshlrev_b32_e32 v10, 2, v3
	v_lshl_add_u64 v[8:9], v[8:9], 0, v[10:11]
	global_store_dwordx4 v[8:9], v[4:7], off offset:1024 sc1 nt

;     __device__ __forceinline__ void kvout(int row, int c, int kv, f32x4 v) const {
;         const int head = c >> 6, g = head >> 2, hs = head & 3, dd = c & 63;
;         if (row < MP) {
;             const int b = row >> 11, t = row & 2047;
;             const int win = g == 0 ? 128 : (g == 1 ? 512 : 2048);
;             const int tw = t - (2048 - win);
;             if (tw >= 0) {
;                 const size_t base = g == 0 ? O2 : (g == 1 ? O3 : O4);
;                 *(f32x4*)(out + base + ((((size_t)l * NB + b) * win + tw) * 2 + kv) * 256 + hs * 64 + dd) = v;
;             }
;         } else if (row < MR) {
;             const int r = row - MP;
;             const size_t base = g == 0 ? O6 : (g == 1 ? O7 : O8);
;             *(f32x4*)(out + base + (((size_t)l * MS + r) * 2 + kv) * 256 + hs * 64 + dd) = v;
;         }
.LBB0_1074:
	v_lshlrev_b32_e32 v10, 2, v54
	v_mov_b32_e32 v11, v2
	v_lshl_add_u64 v[8:9], v[8:9], 0, v[10:11]
	v_lshlrev_b32_e32 v10, 2, v3
	v_lshl_add_u64 v[8:9], v[8:9], 0, v[10:11]
	global_store_dwordx4 v[8:9], v[4:7], off sc1 nt

; __device__ __forceinline__ u32x2 pk4(f32x4 v) { u32x2 r; r.x = pk2(v.x, v.y); r.y = pk2(v.z, v.w); return r; }
;     __device__ __forceinline__ void kvout(int row, int c, int kv, f32x4 v) const {
;         const int head = c >> 6, g = head >> 2, hs = head & 3, dd = c & 63;
;         if (row < MP) {
;             const int b = row >> 11, t = row & 2047;
;             const int win = g == 0 ? 128 : (g == 1 ? 512 : 2048);
;             const int tw = t - (2048 - win);
;             if (tw >= 0) {
;                 const size_t base = g == 0 ? O2 : (g == 1 ? O3 : O4);
;                 *(f32x4*)(out + base + ((((size_t)l * NB + b) * win + tw) * 2 + kv) * 256 + hs * 64 + dd) = v;
;             }
;     __device__ __forceinline__ void operator()(int row, int col, f32x4 v, int fq, float& s1, float& s2) const {
;     ...
;         } else if (col < 2304) {
;             const int c = col - 1536;
;             *(u32x2*)(Vb + (size_t)row * ATT + c) = pk4(v); kvout(row, c, 1, v);
.LBB0_1496:
	s_andn2_saveexec_b64 s[0:1], s[42:43]
	s_cbranch_execz .LBB0_1498
	v_add_u32_e32 v30, 0xfffffa00, v28
	v_mov_b32_e32 v31, v2
	v_cvt_pk_bf16_f32 v32, v4, v5
	v_cvt_pk_bf16_f32 v33, v6, v7
	v_lshl_add_u64 v[34:35], v[30:31], 1, v[12:13]
	global_store_dwordx2 v[34:35], v[32:33], off
	v_and_b32_e32 v25, 0xc0, v28
	v_and_b32_e32 v32, 60, v28
	v_and_b32_e32 v28, 0xffffff00, v30
	v_cmp_eq_u32_e32 vcc, s3, v28
	s_movk_i32 s4, 0xff
	v_mov_b32_e32 v29, v2
	v_cndmask_b32_e32 v28, v223, v224, vcc
	v_cmp_lt_u32_e32 vcc, s4, v30
	v_lshlrev_b32_e32 v30, 2, v25
	s_nop 0
	v_cndmask_b32_e32 v28, v225, v28, vcc
	v_lshlrev_b32_e32 v28, 2, v28
	v_lshl_add_u64 v[28:29], v[14:15], 0, v[28:29]
	v_lshl_add_u64 v[28:29], v[28:29], 0, v[30:31]
	v_lshlrev_b32_e32 v30, 2, v32
	v_lshl_add_u64 v[28:29], v[28:29], 0, v[30:31]
	global_store_dwordx4 v[28:29], v[4:7], off offset:1024 sc1 nt

; __device__ __forceinline__ u32x2 pk4(f32x4 v) { u32x2 r; r.x = pk2(v.x, v.y); r.y = pk2(v.z, v.w); return r; }
;     __device__ __forceinline__ void kvout(int row, int c, int kv, f32x4 v) const {
;         const int head = c >> 6, g = head >> 2, hs = head & 3, dd = c & 63;
;         if (row < MP) {
;             const int b = row >> 11, t = row & 2047;
;             const int win = g == 0 ? 128 : (g == 1 ? 512 : 2048);
;             const int tw = t - (2048 - win);
;             if (tw >= 0) {
;                 const size_t base = g == 0 ? O2 : (g == 1 ? O3 : O4);
;                 *(f32x4*)(out + base + ((((size_t)l * NB + b) * win + tw) * 2 + kv) * 256 + hs * 64 + dd) = v;
;             }
;     __device__ __forceinline__ void operator()(int row, int col, f32x4 v, int fq, float& s1, float& s2) const {
;     ...
;             const bool isk = col >= 768; const int c = isk ? col - 768 : col;
;             if ((c & 48) == 0) {
;                 const int pos = row < MP ? (row & 2047) : 2048 + ((row - MP) & 3);
;                 const float* rt = rope + pos * 16 + (fq & 1) * 4;
;                 const f32x4 cs = *(const f32x4*)rt, sn = *(const f32x4*)(rt + 8);
;                 f32x4 o; o.x = __shfl_xor(v.x, 32); o.y = __shfl_xor(v.y, 32); o.z = __shfl_xor(v.z, 32); o.w = __shfl_xor(v.w, 32);
;                 if (fq < 2) v = v * cs - o * sn; else v = v * cs + o * sn;
;             }
;             if (!isk) { *(u32x2*)(Qb + (size_t)row * ATT + c) = pk4(v * QSCALE); }
;             else { *(u32x2*)(Kb + (size_t)row * ATT + c) = pk4(v); kvout(row, c, 0, v); }
.LBB0_1504:
	s_andn2_saveexec_b64 s[0:1], s[0:1]
	s_cbranch_execz .LBB0_1483
	v_add_u32_e32 v30, 0xfffffd00, v28
	v_mov_b32_e32 v31, v2
	v_cvt_pk_bf16_f32 v32, v4, v5
	v_cvt_pk_bf16_f32 v33, v6, v7
	v_lshl_add_u64 v[34:35], v[30:31], 1, v[20:21]
	global_store_dwordx2 v[34:35], v[32:33], off
	v_and_b32_e32 v25, 0xc0, v28
	v_and_b32_e32 v32, 60, v28
	v_and_b32_e32 v28, 0xffffff00, v30
	v_cmp_eq_u32_e32 vcc, s3, v28
	s_movk_i32 s4, 0xff
	v_mov_b32_e32 v29, v2
	v_cndmask_b32_e32 v28, v223, v224, vcc
	v_cmp_lt_u32_e32 vcc, s4, v30
	v_lshlrev_b32_e32 v30, 2, v25
	s_nop 0
	v_cndmask_b32_e32 v28, v225, v28, vcc
	v_lshlrev_b32_e32 v28, 2, v28
	v_lshl_add_u64 v[28:29], v[14:15], 0, v[28:29]
	v_lshl_add_u64 v[28:29], v[28:29], 0, v[30:31]
	v_lshlrev_b32_e32 v30, 2, v32
	v_lshl_add_u64 v[28:29], v[28:29], 0, v[30:31]
	global_store_dwordx4 v[28:29], v[4:7], off sc1 nt
	s_branch .LBB0_1483

; __device__ __forceinline__ u32x2 pk4(f32x4 v) { u32x2 r; r.x = pk2(v.x, v.y); r.y = pk2(v.z, v.w); return r; }
;     __device__ __forceinline__ void operator()(int row, int col, f32x4 v, int, float&, float&) const { *(u32x2*)(O + (size_t)row * ldc + col) = pk4(v * s); }
;     __device__ __forceinline__ void operator()(const f32x4 (&acc)[2][2][4][2], const Unit& u, int wr, int wc, int fr, int fq) const {
; #pragma unroll
;         for (int bj = 0; bj < 2; ++bj)
; #pragma unroll
;             for (int n = 0; n < 2; ++n) {
;                 const int col = u.pn * BM + bj * HALF + wc * 32 + n * 16 + fq * 4;
; #pragma unroll
;                 for (int ai = 0; ai < 2; ++ai)
; #pragma unroll
;                     for (int m = 0; m < 4; ++m) f(u.pm * BM + ai * HALF + wr * 64 + m * 16 + fr, col, acc[ai][bj][m][n], fq);
;             }
;     }
;     __device__ __forceinline__ void operator()(int row, int col, f32x4 v, int) const {
;         const int c = col;
;         *(f32x4*)(out + O5 + ((size_t)l * 2048 + row) * 2048 + c) = v;
;         *(u32x2*)(mkv + ((size_t)l * 2048 + row) * 2048 + c) = pk4(v);
;     }
.LBB0_1523:
	v_lshl_add_u32 v144, s23, 8, v3
	v_lshl_add_u32 v142, s22, 8, v139
	v_ashrrev_i32_e32 v145, 31, v144
	v_ashrrev_i32_e32 v143, 31, v142
	v_lshlrev_b64 v[146:147], 13, v[144:145]
	v_lshl_add_u64 v[146:147], s[6:7], 0, v[146:147]
	v_lshlrev_b64 v[148:149], 2, v[142:143]
	v_lshl_add_u64 v[146:147], v[146:147], 0, v[148:149]
	global_store_dwordx4 v[146:147], v[128:131], off sc1 nt
	v_lshlrev_b64 v[142:143], 1, v[142:143]
	s_andn2_b64 vcc, exec, s[40:41]
	v_cvt_pk_bf16_f32 v128, v128, v129
	v_cvt_pk_bf16_f32 v129, v130, v131
	v_lshlrev_b64 v[130:131], 12, v[144:145]
	v_lshl_add_u64 v[130:131], s[38:39], 0, v[130:131]
	v_lshl_add_u64 v[130:131], v[130:131], 0, v[142:143]
	global_store_dwordx2 v[130:131], v[128:129], off
	v_or_b32_e32 v128, 16, v144
	v_ashrrev_i32_e32 v129, 31, v128
	v_lshlrev_b64 v[150:151], 13, v[128:129]
	v_lshl_add_u64 v[150:151], s[6:7], 0, v[150:151]
	v_lshl_add_u64 v[150:151], v[150:151], 0, v[148:149]
	global_store_dwordx4 v[150:151], v[124:127], off sc1 nt
	s_mov_b64 s[0:1], -1
	s_nop 0
	v_cvt_pk_bf16_f32 v124, v124, v125
	v_cvt_pk_bf16_f32 v125, v126, v127
	v_lshlrev_b64 v[126:127], 12, v[128:129]
	v_lshl_add_u64 v[126:127], s[38:39], 0, v[126:127]
	v_lshl_add_u64 v[126:127], v[126:127], 0, v[142:143]
	global_store_dwordx2 v[126:127], v[124:125], off
	v_or_b32_e32 v124, 32, v144
	v_ashrrev_i32_e32 v125, 31, v124
	v_lshlrev_b64 v[128:129], 13, v[124:125]
	v_lshl_add_u64 v[128:129], s[6:7], 0, v[128:129]
	v_lshl_add_u64 v[128:129], v[128:129], 0, v[148:149]
	global_store_dwordx4 v[128:129], v[120:123], off sc1 nt
	s_nop 1
	v_cvt_pk_bf16_f32 v120, v120, v121
	v_cvt_pk_bf16_f32 v121, v122, v123
	v_lshlrev_b64 v[122:123], 12, v[124:125]
	v_lshl_add_u64 v[122:123], s[38:39], 0, v[122:123]
	v_lshl_add_u64 v[122:123], v[122:123], 0, v[142:143]
	global_store_dwordx2 v[122:123], v[120:121], off
	v_or_b32_e32 v120, 48, v144
	v_ashrrev_i32_e32 v121, 31, v120
	v_lshlrev_b64 v[124:125], 13, v[120:121]
	v_lshl_add_u64 v[124:125], s[6:7], 0, v[124:125]
	v_lshl_add_u64 v[124:125], v[124:125], 0, v[148:149]
	global_store_dwordx4 v[124:125], v[116:119], off sc1 nt
	s_nop 1
	v_cvt_pk_bf16_f32 v116, v116, v117
	v_cvt_pk_bf16_f32 v117, v118, v119
	v_lshlrev_b64 v[118:119], 12, v[120:121]
	v_lshl_add_u64 v[118:119], s[38:39], 0, v[118:119]
	v_lshl_add_u64 v[118:119], v[118:119], 0, v[142:143]
	global_store_dwordx2 v[118:119], v[116:117], off
	v_add_u32_e32 v116, 0x80, v144
	v_ashrrev_i32_e32 v117, 31, v116
	v_lshlrev_b64 v[120:121], 13, v[116:117]
	v_lshl_add_u64 v[120:121], s[6:7], 0, v[120:121]
	v_lshl_add_u64 v[120:121], v[120:121], 0, v[148:149]
	global_store_dwordx4 v[120:121], v[108:111], off sc1 nt
	s_nop 1
	v_cvt_pk_bf16_f32 v108, v108, v109
	v_cvt_pk_bf16_f32 v109, v110, v111
	v_lshlrev_b64 v[110:111], 12, v[116:117]
	v_lshl_add_u64 v[110:111], s[38:39], 0, v[110:111]
	v_lshl_add_u64 v[110:111], v[110:111], 0, v[142:143]
	global_store_dwordx2 v[110:111], v[108:109], off
	v_add_u32_e32 v108, 0x90, v144
	v_ashrrev_i32_e32 v109, 31, v108
	v_lshlrev_b64 v[116:117], 13, v[108:109]
	v_lshl_add_u64 v[116:117], s[6:7], 0, v[116:117]
	v_lshl_add_u64 v[116:117], v[116:117], 0, v[148:149]
	global_store_dwordx4 v[116:117], v[100:103], off sc1 nt
	s_nop 1
	v_cvt_pk_bf16_f32 v100, v100, v101
	v_cvt_pk_bf16_f32 v101, v102, v103
	v_lshlrev_b64 v[102:103], 12, v[108:109]
	v_lshl_add_u64 v[102:103], s[38:39], 0, v[102:103]
	v_lshl_add_u64 v[102:103], v[102:103], 0, v[142:143]
	global_store_dwordx2 v[102:103], v[100:101], off
	v_add_u32_e32 v100, 0xa0, v144
	v_ashrrev_i32_e32 v101, 31, v100
	v_lshlrev_b64 v[108:109], 13, v[100:101]
	v_lshl_add_u64 v[108:109], s[6:7], 0, v[108:109]
	v_lshl_add_u64 v[108:109], v[108:109], 0, v[148:149]
	global_store_dwordx4 v[108:109], v[88:91], off sc1 nt
	s_nop 1
	v_cvt_pk_bf16_f32 v88, v88, v89
	v_cvt_pk_bf16_f32 v89, v90, v91
	v_lshlrev_b64 v[90:91], 12, v[100:101]
	v_lshl_add_u64 v[90:91], s[38:39], 0, v[90:91]
	v_lshl_add_u64 v[90:91], v[90:91], 0, v[142:143]
	global_store_dwordx2 v[90:91], v[88:89], off
	v_add_u32_e32 v88, 0xb0, v144
	v_ashrrev_i32_e32 v89, 31, v88
	v_lshlrev_b64 v[100:101], 13, v[88:89]
	v_lshl_add_u64 v[100:101], s[6:7], 0, v[100:101]
	v_lshl_add_u64 v[100:101], v[100:101], 0, v[148:149]
	global_store_dwordx4 v[100:101], v[84:87], off sc1 nt
	s_nop 1
	v_cvt_pk_bf16_f32 v84, v84, v85
	v_cvt_pk_bf16_f32 v85, v86, v87
	v_lshlrev_b64 v[86:87], 12, v[88:89]
	v_lshl_add_u64 v[86:87], s[38:39], 0, v[86:87]
	v_lshl_add_u64 v[86:87], v[86:87], 0, v[142:143]
	global_store_dwordx2 v[86:87], v[84:85], off
	global_store_dwordx4 v[146:147], v[112:115], off offset:64 sc1 nt
	v_cvt_pk_bf16_f32 v84, v112, v113
	v_cvt_pk_bf16_f32 v85, v114, v115
; __device__ __forceinline__ u32x2 pk4(f32x4 v) { u32x2 r; r.x = pk2(v.x, v.y); r.y = pk2(v.z, v.w); return r; }
;     __device__ __forceinline__ void operator()(int row, int col, f32x4 v, int, float&, float&) const { *(u32x2*)(O + (size_t)row * ldc + col) = pk4(v * s); }
;     __device__ __forceinline__ void operator()(const f32x4 (&acc)[2][2][4][2], const Unit& u, int wr, int wc, int fr, int fq) const {
; #pragma unroll
;         for (int bj = 0; bj < 2; ++bj)
; #pragma unroll
;             for (int n = 0; n < 2; ++n) {
;                 const int col = u.pn * BM + bj * HALF + wc * 32 + n * 16 + fq * 4;
; #pragma unroll
;                 for (int ai = 0; ai < 2; ++ai)
; #pragma unroll
;                     for (int m = 0; m < 4; ++m) f(u.pm * BM + ai * HALF + wr * 64 + m * 16 + fr, col, acc[ai][bj][m][n], fq);
;             }
;     }
;     __device__ __forceinline__ void operator()(int row, int col, f32x4 v, int) const {
;         const int c = col;
;         *(f32x4*)(out + O5 + ((size_t)l * 2048 + row) * 2048 + c) = v;
;         *(u32x2*)(mkv + ((size_t)l * 2048 + row) * 2048 + c) = pk4(v);
;     }
	global_store_dwordx2 v[130:131], v[84:85], off offset:32
	global_store_dwordx4 v[150:151], v[104:107], off offset:64 sc1 nt
	v_cvt_pk_bf16_f32 v84, v104, v105
	v_cvt_pk_bf16_f32 v85, v106, v107
	global_store_dwordx2 v[126:127], v[84:85], off offset:32
	global_store_dwordx4 v[128:129], v[96:99], off offset:64 sc1 nt
	v_cvt_pk_bf16_f32 v84, v96, v97
	v_cvt_pk_bf16_f32 v85, v98, v99
	global_store_dwordx2 v[122:123], v[84:85], off offset:32
	global_store_dwordx4 v[124:125], v[92:95], off offset:64 sc1 nt
	v_cvt_pk_bf16_f32 v84, v92, v93
	v_cvt_pk_bf16_f32 v85, v94, v95
	global_store_dwordx2 v[118:119], v[84:85], off offset:32
	global_store_dwordx4 v[120:121], v[76:79], off offset:64 sc1 nt
	s_nop 1
	v_cvt_pk_bf16_f32 v76, v76, v77
	v_cvt_pk_bf16_f32 v77, v78, v79
	global_store_dwordx2 v[110:111], v[76:77], off offset:32
	global_store_dwordx4 v[116:117], v[68:71], off offset:64 sc1 nt
	s_nop 1
	v_cvt_pk_bf16_f32 v68, v68, v69
	v_cvt_pk_bf16_f32 v69, v70, v71
	global_store_dwordx2 v[102:103], v[68:69], off offset:32
	global_store_dwordx4 v[108:109], v[60:63], off offset:64 sc1 nt
	s_nop 1
	v_cvt_pk_bf16_f32 v60, v60, v61
	v_cvt_pk_bf16_f32 v61, v62, v63
	global_store_dwordx2 v[90:91], v[60:61], off offset:32
	global_store_dwordx4 v[100:101], v[48:51], off offset:64 sc1 nt
	s_nop 1
	v_cvt_pk_bf16_f32 v48, v48, v49
	v_cvt_pk_bf16_f32 v49, v50, v51
	global_store_dwordx2 v[86:87], v[48:49], off offset:32
	global_store_dwordx4 v[146:147], v[80:83], off offset:512 sc1 nt
	v_cvt_pk_bf16_f32 v48, v80, v81
	v_cvt_pk_bf16_f32 v49, v82, v83
	global_store_dwordx2 v[130:131], v[48:49], off offset:256
	global_store_dwordx4 v[150:151], v[72:75], off offset:512 sc1 nt
	v_cvt_pk_bf16_f32 v48, v72, v73
	v_cvt_pk_bf16_f32 v49, v74, v75
	global_store_dwordx2 v[126:127], v[48:49], off offset:256
	global_store_dwordx4 v[128:129], v[64:67], off offset:512 sc1 nt
	v_cvt_pk_bf16_f32 v48, v64, v65
	v_cvt_pk_bf16_f32 v49, v66, v67
	global_store_dwordx2 v[122:123], v[48:49], off offset:256
	global_store_dwordx4 v[124:125], v[56:59], off offset:512 sc1 nt
	v_cvt_pk_bf16_f32 v48, v56, v57
	v_cvt_pk_bf16_f32 v49, v58, v59
	global_store_dwordx2 v[118:119], v[48:49], off offset:256
	global_store_dwordx4 v[120:121], v[36:39], off offset:512 sc1 nt
	s_nop 1
	v_cvt_pk_bf16_f32 v36, v36, v37
	v_cvt_pk_bf16_f32 v37, v38, v39
	global_store_dwordx2 v[110:111], v[36:37], off offset:256
	global_store_dwordx4 v[116:117], v[28:31], off offset:512 sc1 nt
	s_nop 1
	v_cvt_pk_bf16_f32 v28, v28, v29
	v_cvt_pk_bf16_f32 v29, v30, v31
	global_store_dwordx2 v[102:103], v[28:29], off offset:256
	global_store_dwordx4 v[108:109], v[24:27], off offset:512 sc1 nt
	s_nop 1
	v_cvt_pk_bf16_f32 v24, v24, v25
	v_cvt_pk_bf16_f32 v25, v26, v27
	global_store_dwordx2 v[90:91], v[24:25], off offset:256
	global_store_dwordx4 v[100:101], v[20:23], off offset:512 sc1 nt
	s_nop 1
	v_cvt_pk_bf16_f32 v20, v20, v21
	v_cvt_pk_bf16_f32 v21, v22, v23
	global_store_dwordx2 v[86:87], v[20:21], off offset:256
	global_store_dwordx4 v[146:147], v[52:55], off offset:576 sc1 nt
	v_cvt_pk_bf16_f32 v20, v52, v53
	v_cvt_pk_bf16_f32 v21, v54, v55
	global_store_dwordx2 v[130:131], v[20:21], off offset:288
	global_store_dwordx4 v[150:151], v[44:47], off offset:576 sc1 nt
	v_cvt_pk_bf16_f32 v20, v44, v45
	v_cvt_pk_bf16_f32 v21, v46, v47
	global_store_dwordx2 v[126:127], v[20:21], off offset:288
	global_store_dwordx4 v[128:129], v[40:43], off offset:576 sc1 nt
	v_cvt_pk_bf16_f32 v20, v40, v41
	v_cvt_pk_bf16_f32 v21, v42, v43
	global_store_dwordx2 v[122:123], v[20:21], off offset:288
	global_store_dwordx4 v[124:125], v[32:35], off offset:576 sc1 nt
	v_cvt_pk_bf16_f32 v20, v32, v33
	v_cvt_pk_bf16_f32 v21, v34, v35
	global_store_dwordx2 v[118:119], v[20:21], off offset:288
	global_store_dwordx4 v[120:121], v[16:19], off offset:576 sc1 nt
	s_nop 1
	v_cvt_pk_bf16_f32 v16, v16, v17
	v_cvt_pk_bf16_f32 v17, v18, v19
	global_store_dwordx2 v[110:111], v[16:17], off offset:288
	global_store_dwordx4 v[116:117], v[12:15], off offset:576 sc1 nt
	s_nop 1
	v_cvt_pk_bf16_f32 v12, v12, v13
	v_cvt_pk_bf16_f32 v13, v14, v15
	global_store_dwordx2 v[102:103], v[12:13], off offset:288
	global_store_dwordx4 v[108:109], v[8:11], off offset:576 sc1 nt
	s_nop 1
	v_cvt_pk_bf16_f32 v8, v8, v9
	v_cvt_pk_bf16_f32 v9, v10, v11
	global_store_dwordx2 v[90:91], v[8:9], off offset:288
	global_store_dwordx4 v[100:101], v[4:7], off offset:576 sc1 nt
	s_nop 1
	v_cvt_pk_bf16_f32 v4, v4, v5
	v_cvt_pk_bf16_f32 v5, v6, v7
	global_store_dwordx2 v[86:87], v[4:5], off offset:288
	s_cbranch_vccnz .LBB0_1512
	s_and_b64 vcc, exec, s[36:37]
	s_cbranch_vccnz .LBB0_1511
	s_barrier
	s_branch .LBB0_1511
